# P7 epilogue: U-tile stores in saddr form (32-bit lane offset + SGPR base), 8 fewer 64-bit VALU adds
# speedup vs baseline: 1.0035x; 1.0035x over previous
; __device__ __forceinline__ unsigned cvt_pk_bf16(float lo, float hi) { unsigned r; asm volatile("v_cvt_pk_bf16_f32 %0, %1, %2" : "=v"(r) : "v"(lo), "v"(hi)); return r; }
;     __device__ __forceinline__ void operator()(const f32x4 (&acc)[2][2][4][2], const Unit& u, int wr, int wc, int fr, int fq) const {
;         const int row0 = u.pm * BM + wr * 64 + fr, col0 = u.pn * BM + wc * 32 + 8 * fq, b = (u.pm * BM) >> 12;
;         f32x4 cbv[2][2];
; #pragma unroll
;         for (int bj = 0; bj < 2; ++bj)
; #pragma unroll
;             for (int n = 0; n < 2; ++n) cbv[bj][n] = *(const f32x4*)(cb + (size_t)b * 8192 + col0 + bj * HALF + 4 * n);
; #pragma unroll
;         for (int ai = 0; ai < 2; ++ai)
; #pragma unroll
;             for (int m = 0; m < 4; ++m) { const int rl = wr * 64 + fr + ai * HALF + m * 16; bf16_t* rowp = O + (size_t)(u.pm * BM + rl) * ldc + col0;
;                 const float rs = rstd[((u.pm >> 2) & 1) * 256 + rl];
; #pragma unroll
;                 for (int bj = 0; bj < 2; ++bj) { float v[8];
; #pragma unroll
;                     for (int e = 0; e < 8; ++e) { const float x = fmaxf(acc[ai][bj][m][e >> 2][e & 3] * rs + cbv[bj][e >> 2][e & 3], 0.f); v[e] = x * x; }
;                     u32x4 w; w.x = cvt_pk_bf16(v[0], v[1]); w.y = cvt_pk_bf16(v[2], v[3]); w.z = cvt_pk_bf16(v[4], v[5]); w.w = cvt_pk_bf16(v[6], v[7]);
;                     *(u32x4*)(rowp + bj * HALF) = w; } }
.LBB0_997:
	s_ashr_i32 s24, s22, 4
	s_ashr_i32 s25, s24, 31
	s_lshl_b64 s[24:25], s[24:25], 15
	v_lshl_or_b32 v160, s42, 8, v171
	s_add_u32 s24, s36, s24
	s_addc_u32 s25, s37, s25
	v_ashrrev_i32_e32 v161, 31, v160
	v_lshl_add_u64 v[128:129], v[160:161], 2, s[24:25]
	global_load_dwordx4 v[140:143], v[128:129], off
	global_load_dwordx4 v[136:139], v[128:129], off offset:16
	global_load_dwordx4 v[132:135], v[128:129], off offset:512
	s_nop 0
	global_load_dwordx4 v[128:131], v[128:129], off offset:528
	s_lshl_b32 s15, s22, 8
	s_and_b32 s17, s15, 0x400
	v_add_u32_e32 v176, s17, v172
	ds_read_b32 v177, v176
	v_add_u32_e32 v178, s15, v162
	v_ashrrev_i32_e32 v179, 31, v178
	v_lshlrev_b64 v[178:179], 14, v[178:179]
	v_lshlrev_b64 v[160:161], 1, v[160:161]
	v_add_u32_e32 v178, v178, v160
	v_add_u32_e32 v180, s15, v164
	v_ashrrev_i32_e32 v181, 31, v180
	s_andn2_b64 vcc, exec, s[4:5]
	s_mov_b64 s[4:5], -1
	s_waitcnt vmcnt(0) lgkmcnt(0)
	v_fma_f32 v124, v124, v177, v140
	v_fma_f32 v125, v125, v177, v141
	v_fma_f32 v126, v126, v177, v142
	v_fma_f32 v127, v127, v177, v143
	v_fma_f32 v120, v120, v177, v136
	v_fma_f32 v121, v121, v177, v137
	v_fma_f32 v122, v122, v177, v138
	v_fma_f32 v123, v123, v177, v139
	v_fma_f32 v118, v118, v177, v134
	v_fma_f32 v112, v112, v177, v128
	v_fma_f32 v113, v113, v177, v129
	v_fma_f32 v114, v114, v177, v130
	v_fma_f32 v115, v115, v177, v131
	v_fma_f32 v116, v116, v177, v132
	v_fma_f32 v117, v117, v177, v133
	v_fma_f32 v119, v119, v177, v135
	v_max_f32_e32 v124, 0, v124
	v_max_f32_e32 v125, 0, v125
	v_max_f32_e32 v126, 0, v126
	v_max_f32_e32 v127, 0, v127
	v_max_f32_e32 v120, 0, v120
	v_max_f32_e32 v121, 0, v121
	v_max_f32_e32 v122, 0, v122
	v_max_f32_e32 v123, 0, v123
	v_max_f32_e32 v118, 0, v118
	v_max_f32_e32 v112, 0, v112
	v_max_f32_e32 v113, 0, v113
	v_max_f32_e32 v114, 0, v114
	v_max_f32_e32 v115, 0, v115
	v_max_f32_e32 v116, 0, v116
	v_max_f32_e32 v117, 0, v117
	v_max_f32_e32 v119, 0, v119
	v_mul_f32_e32 v124, v124, v124
	v_mul_f32_e32 v125, v125, v125
	v_mul_f32_e32 v126, v126, v126
	v_mul_f32_e32 v127, v127, v127
	v_mul_f32_e32 v120, v120, v120
	v_mul_f32_e32 v121, v121, v121
	v_mul_f32_e32 v122, v122, v122
	v_mul_f32_e32 v123, v123, v123
	v_mul_f32_e32 v118, v118, v118
	v_mul_f32_e32 v177, v112, v112
	v_mul_f32_e32 v182, v113, v113
	v_mul_f32_e32 v183, v114, v114
	v_mul_f32_e32 v184, v115, v115
	v_cvt_pk_bf16_f32 v112, v124, v125
	v_cvt_pk_bf16_f32 v113, v126, v127
	v_cvt_pk_bf16_f32 v114, v120, v121
	v_cvt_pk_bf16_f32 v115, v122, v123
	v_mul_f32_e32 v116, v116, v116
	v_mul_f32_e32 v117, v117, v117
	v_mul_f32_e32 v119, v119, v119
	global_store_dwordx4 v178, v[112:115], s[72:73]
	s_nop 1
	v_cvt_pk_bf16_f32 v112, v116, v117
	v_cvt_pk_bf16_f32 v113, v118, v119
	v_cvt_pk_bf16_f32 v114, v177, v182
	v_cvt_pk_bf16_f32 v115, v183, v184
	ds_read_b32 v118, v176 offset:64
	global_store_dwordx4 v178, v[112:115], s[72:73] offset:256
	v_lshlrev_b64 v[116:117], 14, v[180:181]
	v_add_u32_e32 v116, v116, v160
	s_waitcnt lgkmcnt(0)
	v_fma_f32 v104, v104, v118, v136
	v_max_f32_e32 v104, 0, v104
	v_mul_f32_e32 v112, v104, v104
	v_fma_f32 v104, v105, v118, v137
	v_max_f32_e32 v104, 0, v104
	v_mul_f32_e32 v113, v104, v104
	v_fma_f32 v104, v106, v118, v138
	v_max_f32_e32 v104, 0, v104
	v_fma_f32 v108, v108, v118, v140
	v_fma_f32 v109, v109, v118, v141
	v_mul_f32_e32 v114, v104, v104
	v_fma_f32 v104, v107, v118, v139
	v_fma_f32 v110, v110, v118, v142
	v_fma_f32 v111, v111, v118, v143
	v_max_f32_e32 v108, 0, v108
	v_max_f32_e32 v109, 0, v109
	v_max_f32_e32 v104, 0, v104
	v_fma_f32 v96, v96, v118, v128
	v_max_f32_e32 v110, 0, v110
	v_max_f32_e32 v111, 0, v111
	v_mul_f32_e32 v108, v108, v108
	v_mul_f32_e32 v109, v109, v109
	v_mul_f32_e32 v107, v104, v104
	v_cvt_pk_bf16_f32 v104, v108, v109
	v_max_f32_e32 v96, 0, v96
	v_mul_f32_e32 v110, v110, v110
	v_mul_f32_e32 v111, v111, v111
	v_cvt_pk_bf16_f32 v105, v110, v111
	v_cvt_pk_bf16_f32 v106, v112, v113
	v_cvt_pk_bf16_f32 v107, v114, v107
	global_store_dwordx4 v116, v[104:107], s[72:73]
	v_fma_f32 v100, v100, v118, v132
	v_fma_f32 v101, v101, v118, v133
	v_mul_f32_e32 v104, v96, v96
	v_fma_f32 v96, v97, v118, v129
	v_max_f32_e32 v96, 0, v96
	v_mul_f32_e32 v105, v96, v96
	v_fma_f32 v96, v98, v118, v130
	v_max_f32_e32 v96, 0, v96
	v_fma_f32 v102, v102, v118, v134
	v_fma_f32 v103, v103, v118, v135
	v_mul_f32_e32 v106, v96, v96
	v_fma_f32 v96, v99, v118, v131
	v_max_f32_e32 v100, 0, v100
	v_max_f32_e32 v101, 0, v101
	v_max_f32_e32 v102, 0, v102
	v_max_f32_e32 v103, 0, v103
	v_max_f32_e32 v96, 0, v96
	v_mul_f32_e32 v100, v100, v100
	v_mul_f32_e32 v101, v101, v101
	v_mul_f32_e32 v102, v102, v102
	v_mul_f32_e32 v103, v103, v103
	v_mul_f32_e32 v99, v96, v96
	v_cvt_pk_bf16_f32 v96, v100, v101
	v_cvt_pk_bf16_f32 v97, v102, v103
	v_cvt_pk_bf16_f32 v98, v104, v105
	v_cvt_pk_bf16_f32 v99, v106, v99
	global_store_dwordx4 v116, v[96:99], s[72:73] offset:256
	ds_read_b32 v98, v176 offset:128
	s_waitcnt lgkmcnt(0)
; __device__ __forceinline__ unsigned cvt_pk_bf16(float lo, float hi) { unsigned r; asm volatile("v_cvt_pk_bf16_f32 %0, %1, %2" : "=v"(r) : "v"(lo), "v"(hi)); return r; }
;     __device__ __forceinline__ void operator()(const f32x4 (&acc)[2][2][4][2], const Unit& u, int wr, int wc, int fr, int fq) const {
;     ...
;             for (int m = 0; m < 4; ++m) { const int rl = wr * 64 + fr + ai * HALF + m * 16; bf16_t* rowp = O + (size_t)(u.pm * BM + rl) * ldc + col0;
;                 const float rs = rstd[((u.pm >> 2) & 1) * 256 + rl];
; #pragma unroll
;                 for (int bj = 0; bj < 2; ++bj) { float v[8];
; #pragma unroll
;                     for (int e = 0; e < 8; ++e) { const float x = fmaxf(acc[ai][bj][m][e >> 2][e & 3] * rs + cbv[bj][e >> 2][e & 3], 0.f); v[e] = x * x; }
;                     u32x4 w; w.x = cvt_pk_bf16(v[0], v[1]); w.y = cvt_pk_bf16(v[2], v[3]); w.z = cvt_pk_bf16(v[4], v[5]); w.w = cvt_pk_bf16(v[6], v[7]);
;                     *(u32x4*)(rowp + bj * HALF) = w; } }
	v_fma_f32 v88, v88, v98, v136
	v_max_f32_e32 v88, 0, v88
	v_mul_f32_e32 v99, v88, v88
	v_fma_f32 v88, v89, v98, v137
	v_max_f32_e32 v88, 0, v88
	v_add_u32_e32 v96, s15, v165
	v_mul_f32_e32 v100, v88, v88
	v_fma_f32 v88, v90, v98, v138
	v_ashrrev_i32_e32 v97, 31, v96
	v_max_f32_e32 v88, 0, v88
	v_lshlrev_b64 v[96:97], 14, v[96:97]
	v_fma_f32 v92, v92, v98, v140
	v_fma_f32 v93, v93, v98, v141
	v_mul_f32_e32 v101, v88, v88
	v_fma_f32 v88, v91, v98, v139
	v_max_f32_e32 v92, 0, v92
	v_max_f32_e32 v93, 0, v93
	v_fma_f32 v94, v94, v98, v142
	v_fma_f32 v95, v95, v98, v143
	v_max_f32_e32 v88, 0, v88
	v_fma_f32 v80, v80, v98, v128
	v_add_u32_e32 v96, v96, v160
	v_mul_f32_e32 v92, v92, v92
	v_mul_f32_e32 v93, v93, v93
	v_max_f32_e32 v94, 0, v94
	v_max_f32_e32 v95, 0, v95
	v_mul_f32_e32 v91, v88, v88
	v_cvt_pk_bf16_f32 v88, v92, v93
	v_max_f32_e32 v80, 0, v80
	v_mul_f32_e32 v94, v94, v94
	v_mul_f32_e32 v95, v95, v95
	v_cvt_pk_bf16_f32 v89, v94, v95
	v_cvt_pk_bf16_f32 v90, v99, v100
	v_cvt_pk_bf16_f32 v91, v101, v91
	global_store_dwordx4 v96, v[88:91], s[72:73]
	v_fma_f32 v84, v84, v98, v132
	v_fma_f32 v85, v85, v98, v133
	v_mul_f32_e32 v88, v80, v80
	v_fma_f32 v80, v81, v98, v129
	v_max_f32_e32 v80, 0, v80
	v_mul_f32_e32 v89, v80, v80
	v_fma_f32 v80, v82, v98, v130
	v_max_f32_e32 v80, 0, v80
	v_fma_f32 v86, v86, v98, v134
	v_fma_f32 v87, v87, v98, v135
	v_mul_f32_e32 v90, v80, v80
	v_fma_f32 v80, v83, v98, v131
	v_max_f32_e32 v84, 0, v84
	v_max_f32_e32 v85, 0, v85
	v_max_f32_e32 v86, 0, v86
	v_max_f32_e32 v87, 0, v87
	v_max_f32_e32 v80, 0, v80
	v_mul_f32_e32 v84, v84, v84
	v_mul_f32_e32 v85, v85, v85
	v_mul_f32_e32 v86, v86, v86
	v_mul_f32_e32 v87, v87, v87
	v_mul_f32_e32 v83, v80, v80
	v_cvt_pk_bf16_f32 v80, v84, v85
	v_cvt_pk_bf16_f32 v81, v86, v87
	v_cvt_pk_bf16_f32 v82, v88, v89
	v_cvt_pk_bf16_f32 v83, v90, v83
	global_store_dwordx4 v96, v[80:83], s[72:73] offset:256
	ds_read_b32 v82, v176 offset:192
	s_waitcnt lgkmcnt(0)
	v_fma_f32 v72, v72, v82, v136
	v_max_f32_e32 v72, 0, v72
	v_mul_f32_e32 v83, v72, v72
	v_fma_f32 v72, v73, v82, v137
	v_max_f32_e32 v72, 0, v72
	v_add_u32_e32 v80, s15, v166
	v_mul_f32_e32 v84, v72, v72
	v_fma_f32 v72, v74, v82, v138
	v_ashrrev_i32_e32 v81, 31, v80
	v_max_f32_e32 v72, 0, v72
	v_lshlrev_b64 v[80:81], 14, v[80:81]
	v_fma_f32 v76, v76, v82, v140
	v_fma_f32 v77, v77, v82, v141
	v_mul_f32_e32 v85, v72, v72
	v_fma_f32 v72, v75, v82, v139
	v_max_f32_e32 v76, 0, v76
	v_max_f32_e32 v77, 0, v77
	v_fma_f32 v78, v78, v82, v142
	v_fma_f32 v79, v79, v82, v143
	v_max_f32_e32 v72, 0, v72
	v_fma_f32 v64, v64, v82, v128
	v_add_u32_e32 v80, v80, v160
	v_mul_f32_e32 v76, v76, v76
	v_mul_f32_e32 v77, v77, v77
	v_max_f32_e32 v78, 0, v78
	v_max_f32_e32 v79, 0, v79
	v_mul_f32_e32 v75, v72, v72
	v_cvt_pk_bf16_f32 v72, v76, v77
	v_max_f32_e32 v64, 0, v64
	v_mul_f32_e32 v78, v78, v78
	v_mul_f32_e32 v79, v79, v79
	v_cvt_pk_bf16_f32 v73, v78, v79
	v_cvt_pk_bf16_f32 v74, v83, v84
	v_cvt_pk_bf16_f32 v75, v85, v75
	global_store_dwordx4 v80, v[72:75], s[72:73]
	v_fma_f32 v68, v68, v82, v132
	v_fma_f32 v69, v69, v82, v133
	v_mul_f32_e32 v72, v64, v64
	v_fma_f32 v64, v65, v82, v129
	v_max_f32_e32 v64, 0, v64
	v_mul_f32_e32 v73, v64, v64
	v_fma_f32 v64, v66, v82, v130
	v_max_f32_e32 v64, 0, v64
	v_fma_f32 v70, v70, v82, v134
	v_fma_f32 v71, v71, v82, v135
	v_mul_f32_e32 v74, v64, v64
	v_fma_f32 v64, v67, v82, v131
	v_max_f32_e32 v68, 0, v68
	v_max_f32_e32 v69, 0, v69
	v_max_f32_e32 v70, 0, v70
	v_max_f32_e32 v71, 0, v71
	v_max_f32_e32 v64, 0, v64
	v_mul_f32_e32 v68, v68, v68
	v_mul_f32_e32 v69, v69, v69
	v_mul_f32_e32 v70, v70, v70
	v_mul_f32_e32 v71, v71, v71
	v_mul_f32_e32 v67, v64, v64
	v_cvt_pk_bf16_f32 v64, v68, v69
	v_cvt_pk_bf16_f32 v65, v70, v71
	v_cvt_pk_bf16_f32 v66, v72, v73
	v_cvt_pk_bf16_f32 v67, v74, v67
	global_store_dwordx4 v80, v[64:67], s[72:73] offset:256
	ds_read_b32 v66, v176 offset:512
	s_waitcnt lgkmcnt(0)
	v_fma_f32 v56, v56, v66, v136
	v_max_f32_e32 v56, 0, v56
	v_mul_f32_e32 v67, v56, v56
	v_fma_f32 v56, v57, v66, v137
	v_max_f32_e32 v56, 0, v56
	v_add_u32_e32 v64, s15, v167
	v_mul_f32_e32 v68, v56, v56
	v_fma_f32 v56, v58, v66, v138
	v_ashrrev_i32_e32 v65, 31, v64
	v_max_f32_e32 v56, 0, v56
	v_lshlrev_b64 v[64:65], 14, v[64:65]
	v_fma_f32 v60, v60, v66, v140
	v_fma_f32 v61, v61, v66, v141
	v_mul_f32_e32 v69, v56, v56
	v_fma_f32 v56, v59, v66, v139
	v_max_f32_e32 v60, 0, v60
	v_max_f32_e32 v61, 0, v61
	v_fma_f32 v62, v62, v66, v142
	v_fma_f32 v63, v63, v66, v143
	v_max_f32_e32 v56, 0, v56
	v_fma_f32 v48, v48, v66, v128
	v_add_u32_e32 v64, v64, v160
	v_mul_f32_e32 v60, v60, v60
	v_mul_f32_e32 v61, v61, v61
	v_max_f32_e32 v62, 0, v62
	v_max_f32_e32 v63, 0, v63
	v_mul_f32_e32 v59, v56, v56
	v_cvt_pk_bf16_f32 v56, v60, v61
	v_max_f32_e32 v48, 0, v48
	v_mul_f32_e32 v62, v62, v62
	v_mul_f32_e32 v63, v63, v63
	v_cvt_pk_bf16_f32 v57, v62, v63
	v_cvt_pk_bf16_f32 v58, v67, v68
	v_cvt_pk_bf16_f32 v59, v69, v59
	global_store_dwordx4 v64, v[56:59], s[72:73]
	v_fma_f32 v52, v52, v66, v132
	v_fma_f32 v53, v53, v66, v133
	v_mul_f32_e32 v56, v48, v48
	v_fma_f32 v48, v49, v66, v129
	v_max_f32_e32 v48, 0, v48
	v_mul_f32_e32 v57, v48, v48
	v_fma_f32 v48, v50, v66, v130
	v_max_f32_e32 v48, 0, v48
	v_fma_f32 v54, v54, v66, v134
	v_fma_f32 v55, v55, v66, v135
	v_mul_f32_e32 v58, v48, v48
	v_fma_f32 v48, v51, v66, v131
	v_max_f32_e32 v52, 0, v52
	v_max_f32_e32 v53, 0, v53
	v_max_f32_e32 v54, 0, v54
	v_max_f32_e32 v55, 0, v55
	v_max_f32_e32 v48, 0, v48
	v_mul_f32_e32 v52, v52, v52
	v_mul_f32_e32 v53, v53, v53
	v_mul_f32_e32 v54, v54, v54
	v_mul_f32_e32 v55, v55, v55
	v_mul_f32_e32 v51, v48, v48
	v_cvt_pk_bf16_f32 v48, v52, v53
	v_cvt_pk_bf16_f32 v49, v54, v55
	v_cvt_pk_bf16_f32 v50, v56, v57
	v_cvt_pk_bf16_f32 v51, v58, v51
	global_store_dwordx4 v64, v[48:51], s[72:73] offset:256
	ds_read_b32 v50, v176 offset:576
	s_waitcnt lgkmcnt(0)
; __device__ __forceinline__ unsigned cvt_pk_bf16(float lo, float hi) { unsigned r; asm volatile("v_cvt_pk_bf16_f32 %0, %1, %2" : "=v"(r) : "v"(lo), "v"(hi)); return r; }
; #define PG8_BAR __builtin_amdgcn_s_barrier()
;     __device__ __forceinline__ void operator()(const f32x4 (&acc)[2][2][4][2], const Unit& u, int wr, int wc, int fr, int fq) const {
;     ...
;             for (int m = 0; m < 4; ++m) { const int rl = wr * 64 + fr + ai * HALF + m * 16; bf16_t* rowp = O + (size_t)(u.pm * BM + rl) * ldc + col0;
;                 const float rs = rstd[((u.pm >> 2) & 1) * 256 + rl];
; #pragma unroll
;                 for (int bj = 0; bj < 2; ++bj) { float v[8];
; #pragma unroll
;                     for (int e = 0; e < 8; ++e) { const float x = fmaxf(acc[ai][bj][m][e >> 2][e & 3] * rs + cbv[bj][e >> 2][e & 3], 0.f); v[e] = x * x; }
;                     u32x4 w; w.x = cvt_pk_bf16(v[0], v[1]); w.y = cvt_pk_bf16(v[2], v[3]); w.z = cvt_pk_bf16(v[4], v[5]); w.w = cvt_pk_bf16(v[6], v[7]);
;                     *(u32x4*)(rowp + bj * HALF) = w; } }
; template <class Epi, class Sched, bool ALIGN_EPI = false, bool SP2 = false>
; __device__ __forceinline__ void gemm_phase(PG8_LAS unsigned char* lds, const Gemm g, const Sched& S, const Epi& E) {
;     ...
;         if (!has_next) break;
; #pragma unroll
;         for (int a = 0; a < 2; ++a)
; #pragma unroll
;             for (int b = 0; b < 2; ++b)
; #pragma unroll
;                 for (int m = 0; m < 4; ++m)
; #pragma unroll
;                     for (int n = 0; n < 2; ++n) acc[a][b][m][n] = (f32x4){0.f, 0.f, 0.f, 0.f};
;         cur = nxt; cA = nA; cB = nB; ++ui;
;         if constexpr (ALIGN_EPI) { if (wr == 1) PG8_BAR; }
	v_fma_f32 v40, v40, v50, v136
	v_max_f32_e32 v40, 0, v40
	v_mul_f32_e32 v51, v40, v40
	v_fma_f32 v40, v41, v50, v137
	v_max_f32_e32 v40, 0, v40
	v_add_u32_e32 v48, s15, v168
	v_mul_f32_e32 v52, v40, v40
	v_fma_f32 v40, v42, v50, v138
	v_ashrrev_i32_e32 v49, 31, v48
	v_max_f32_e32 v40, 0, v40
	v_lshlrev_b64 v[48:49], 14, v[48:49]
	v_fma_f32 v44, v44, v50, v140
	v_fma_f32 v45, v45, v50, v141
	v_mul_f32_e32 v53, v40, v40
	v_fma_f32 v40, v43, v50, v139
	v_max_f32_e32 v44, 0, v44
	v_max_f32_e32 v45, 0, v45
	v_fma_f32 v46, v46, v50, v142
	v_fma_f32 v47, v47, v50, v143
	v_max_f32_e32 v40, 0, v40
	v_fma_f32 v32, v32, v50, v128
	v_add_u32_e32 v48, v48, v160
	v_mul_f32_e32 v44, v44, v44
	v_mul_f32_e32 v45, v45, v45
	v_max_f32_e32 v46, 0, v46
	v_max_f32_e32 v47, 0, v47
	v_mul_f32_e32 v43, v40, v40
	v_cvt_pk_bf16_f32 v40, v44, v45
	v_max_f32_e32 v32, 0, v32
	v_mul_f32_e32 v46, v46, v46
	v_mul_f32_e32 v47, v47, v47
	v_cvt_pk_bf16_f32 v41, v46, v47
	v_cvt_pk_bf16_f32 v42, v51, v52
	v_cvt_pk_bf16_f32 v43, v53, v43
	global_store_dwordx4 v48, v[40:43], s[72:73]
	v_fma_f32 v36, v36, v50, v132
	v_fma_f32 v37, v37, v50, v133
	v_mul_f32_e32 v40, v32, v32
	v_fma_f32 v32, v33, v50, v129
	v_max_f32_e32 v32, 0, v32
	v_mul_f32_e32 v41, v32, v32
	v_fma_f32 v32, v34, v50, v130
	v_max_f32_e32 v32, 0, v32
	v_fma_f32 v38, v38, v50, v134
	v_fma_f32 v39, v39, v50, v135
	v_mul_f32_e32 v42, v32, v32
	v_fma_f32 v32, v35, v50, v131
	v_max_f32_e32 v36, 0, v36
	v_max_f32_e32 v37, 0, v37
	v_max_f32_e32 v38, 0, v38
	v_max_f32_e32 v39, 0, v39
	v_max_f32_e32 v32, 0, v32
	v_mul_f32_e32 v36, v36, v36
	v_mul_f32_e32 v37, v37, v37
	v_mul_f32_e32 v38, v38, v38
	v_mul_f32_e32 v39, v39, v39
	v_mul_f32_e32 v35, v32, v32
	v_cvt_pk_bf16_f32 v32, v36, v37
	v_cvt_pk_bf16_f32 v33, v38, v39
	v_cvt_pk_bf16_f32 v34, v40, v41
	v_cvt_pk_bf16_f32 v35, v42, v35
	global_store_dwordx4 v48, v[32:35], s[72:73] offset:256
	ds_read_b32 v34, v176 offset:640
	s_waitcnt lgkmcnt(0)
	v_fma_f32 v24, v24, v34, v136
	v_max_f32_e32 v24, 0, v24
	v_mul_f32_e32 v35, v24, v24
	v_fma_f32 v24, v25, v34, v137
	v_max_f32_e32 v24, 0, v24
	v_add_u32_e32 v32, s15, v169
	v_mul_f32_e32 v36, v24, v24
	v_fma_f32 v24, v26, v34, v138
	v_ashrrev_i32_e32 v33, 31, v32
	v_max_f32_e32 v24, 0, v24
	v_lshlrev_b64 v[32:33], 14, v[32:33]
	v_fma_f32 v28, v28, v34, v140
	v_fma_f32 v29, v29, v34, v141
	v_mul_f32_e32 v37, v24, v24
	v_fma_f32 v24, v27, v34, v139
	v_max_f32_e32 v28, 0, v28
	v_max_f32_e32 v29, 0, v29
	v_fma_f32 v30, v30, v34, v142
	v_fma_f32 v31, v31, v34, v143
	v_max_f32_e32 v24, 0, v24
	v_fma_f32 v16, v16, v34, v128
	v_add_u32_e32 v32, v32, v160
	v_mul_f32_e32 v28, v28, v28
	v_mul_f32_e32 v29, v29, v29
	v_max_f32_e32 v30, 0, v30
	v_max_f32_e32 v31, 0, v31
	v_mul_f32_e32 v27, v24, v24
	v_cvt_pk_bf16_f32 v24, v28, v29
	v_max_f32_e32 v16, 0, v16
	v_mul_f32_e32 v30, v30, v30
	v_mul_f32_e32 v31, v31, v31
	v_cvt_pk_bf16_f32 v25, v30, v31
	v_cvt_pk_bf16_f32 v26, v35, v36
	v_cvt_pk_bf16_f32 v27, v37, v27
	global_store_dwordx4 v32, v[24:27], s[72:73]
	v_fma_f32 v20, v20, v34, v132
	v_fma_f32 v21, v21, v34, v133
	v_mul_f32_e32 v24, v16, v16
	v_fma_f32 v16, v17, v34, v129
	v_max_f32_e32 v16, 0, v16
	v_mul_f32_e32 v25, v16, v16
	v_fma_f32 v16, v18, v34, v130
	v_max_f32_e32 v16, 0, v16
	v_fma_f32 v22, v22, v34, v134
	v_fma_f32 v23, v23, v34, v135
	v_mul_f32_e32 v26, v16, v16
	v_fma_f32 v16, v19, v34, v131
	v_max_f32_e32 v20, 0, v20
	v_max_f32_e32 v21, 0, v21
	v_max_f32_e32 v22, 0, v22
	v_max_f32_e32 v23, 0, v23
	v_max_f32_e32 v16, 0, v16
	v_mul_f32_e32 v20, v20, v20
	v_mul_f32_e32 v21, v21, v21
	v_mul_f32_e32 v22, v22, v22
	v_mul_f32_e32 v23, v23, v23
	v_mul_f32_e32 v19, v16, v16
	v_cvt_pk_bf16_f32 v16, v20, v21
	v_cvt_pk_bf16_f32 v17, v22, v23
	v_cvt_pk_bf16_f32 v18, v24, v25
	v_cvt_pk_bf16_f32 v19, v26, v19
	global_store_dwordx4 v32, v[16:19], s[72:73] offset:256
	ds_read_b32 v18, v176 offset:704
	s_waitcnt lgkmcnt(0)
	v_fma_f32 v8, v8, v18, v136
	v_max_f32_e32 v8, 0, v8
	v_mul_f32_e32 v19, v8, v8
	v_fma_f32 v8, v9, v18, v137
	v_add_u32_e32 v16, s15, v170
	v_max_f32_e32 v8, 0, v8
	v_ashrrev_i32_e32 v17, 31, v16
	v_mul_f32_e32 v20, v8, v8
	v_fma_f32 v8, v10, v18, v138
	v_lshlrev_b64 v[16:17], 14, v[16:17]
	v_fma_f32 v12, v12, v18, v140
	v_fma_f32 v13, v13, v18, v141
	v_max_f32_e32 v8, 0, v8
	v_fmac_f32_e32 v139, v11, v18
	v_max_f32_e32 v12, 0, v12
	v_max_f32_e32 v13, 0, v13
	v_fma_f32 v14, v14, v18, v142
	v_fmac_f32_e32 v143, v15, v18
	v_mul_f32_e32 v21, v8, v8
	v_max_f32_e32 v8, 0, v139
	v_fma_f32 v0, v0, v18, v128
	v_add_u32_e32 v16, v16, v160
	v_mul_f32_e32 v12, v12, v12
	v_mul_f32_e32 v13, v13, v13
	v_max_f32_e32 v14, 0, v14
	v_max_f32_e32 v15, 0, v143
	v_mul_f32_e32 v11, v8, v8
	v_cvt_pk_bf16_f32 v8, v12, v13
	v_max_f32_e32 v0, 0, v0
	v_mul_f32_e32 v14, v14, v14
	v_mul_f32_e32 v15, v15, v15
	v_cvt_pk_bf16_f32 v9, v14, v15
	v_cvt_pk_bf16_f32 v10, v19, v20
	v_cvt_pk_bf16_f32 v11, v21, v11
	global_store_dwordx4 v16, v[8:11], s[72:73]
	v_fmac_f32_e32 v131, v3, v18
	v_fma_f32 v4, v4, v18, v132
	v_mul_f32_e32 v8, v0, v0
	v_fma_f32 v0, v1, v18, v129
	v_max_f32_e32 v0, 0, v0
	v_mul_f32_e32 v9, v0, v0
	v_fma_f32 v0, v2, v18, v130
	v_max_f32_e32 v0, 0, v0
	v_fma_f32 v5, v5, v18, v133
	v_fma_f32 v6, v6, v18, v134
	v_fmac_f32_e32 v135, v7, v18
	v_mul_f32_e32 v10, v0, v0
	v_max_f32_e32 v0, 0, v131
	v_max_f32_e32 v4, 0, v4
	v_max_f32_e32 v5, 0, v5
	v_max_f32_e32 v6, 0, v6
	v_max_f32_e32 v7, 0, v135
	v_mul_f32_e32 v3, v0, v0
	v_mul_f32_e32 v4, v4, v4
	v_mul_f32_e32 v5, v5, v5
	v_mul_f32_e32 v6, v6, v6
	v_mul_f32_e32 v7, v7, v7
	v_cvt_pk_bf16_f32 v0, v4, v5
	v_cvt_pk_bf16_f32 v1, v6, v7
	v_cvt_pk_bf16_f32 v2, v8, v9
	v_cvt_pk_bf16_f32 v3, v10, v3
	global_store_dwordx4 v16, v[0:3], s[72:73] offset:256
	s_cbranch_vccnz .LBB0_986
	s_andn2_b64 vcc, exec, s[6:7]
	s_cbranch_vccnz .LBB0_985
	s_barrier
	s_branch .LBB0_985
